# convert_layer p[layer] f32->bf16 copy: 9 iterations' loads requested together (clamped when out of range) instead of one load pair per round trip
# baseline (speedup 1.0000x reference)
; __device__ __forceinline__ u32x4 pack8(const f32x4 a, const f32x4 b) { u32x4 w; w.x = cvt_pk_bf16(a[0], a[1]); w.y = cvt_pk_bf16(a[2], a[3]); w.z = cvt_pk_bf16(b[0], b[1]); w.w = cvt_pk_bf16(b[2], b[3]); return w; }
; __device__ __forceinline__ void convert_layer(unsigned char* smem, const Params& P, int layer, int skip) {
;     ...
;     const f32x4* ps = (const f32x4*)(P.p + (size_t)layer * T_TOK * 256); u32x4* pd = (u32x4*)(P.ws + OFF_PB + (size_t)(layer & 1) * PB_BYTES);
;     for (size_t i = (size_t)vb * 512 + tidx; i < (size_t)T_TOK * 256 / 8; i += (size_t)vG * 512) pd[i] = pack8(ps[2 * i], ps[2 * i + 1]);
.Lpcv_pass:
	s_mov_b64 s[6:7], exec
	s_mov_b64 s[4:5], 0xfffff
	v_lshl_add_u64 v[16:17], v[2:3], 0, s[10:11]
	v_mov_b32_e32 v14, 1
	global_load_dwordx4 v[20:23], v[16:17], off
	global_load_dwordx4 v[24:27], v[16:17], off offset:16
	v_lshl_add_u64 v[8:9], v[8:9], 0, s[44:45]
	v_lshl_add_u64 v[2:3], v[2:3], 0, s[12:13]
	v_cmp_ge_u64_e32 vcc, s[4:5], v[8:9]
	v_lshl_add_u64 v[12:13], v[2:3], 0, s[10:11]
	s_nop 1
	v_cndmask_b32_e64 v15, 0, 1, vcc
	v_cndmask_b32_e32 v12, v16, v12, vcc
	v_cndmask_b32_e32 v13, v17, v13, vcc
	v_add_u32_e32 v14, v14, v15
	global_load_dwordx4 v[28:31], v[12:13], off
	global_load_dwordx4 v[32:35], v[12:13], off offset:16
	v_lshl_add_u64 v[8:9], v[8:9], 0, s[44:45]
	v_lshl_add_u64 v[2:3], v[2:3], 0, s[12:13]
	v_cmp_ge_u64_e32 vcc, s[4:5], v[8:9]
	v_lshl_add_u64 v[12:13], v[2:3], 0, s[10:11]
	s_nop 1
	v_cndmask_b32_e64 v15, 0, 1, vcc
	v_cndmask_b32_e32 v12, v16, v12, vcc
	v_cndmask_b32_e32 v13, v17, v13, vcc
	v_add_u32_e32 v14, v14, v15
	global_load_dwordx4 v[36:39], v[12:13], off
	global_load_dwordx4 v[40:43], v[12:13], off offset:16
	v_lshl_add_u64 v[8:9], v[8:9], 0, s[44:45]
	v_lshl_add_u64 v[2:3], v[2:3], 0, s[12:13]
	v_cmp_ge_u64_e32 vcc, s[4:5], v[8:9]
	v_lshl_add_u64 v[12:13], v[2:3], 0, s[10:11]
	s_nop 1
	v_cndmask_b32_e64 v15, 0, 1, vcc
	v_cndmask_b32_e32 v12, v16, v12, vcc
	v_cndmask_b32_e32 v13, v17, v13, vcc
	v_add_u32_e32 v14, v14, v15
	global_load_dwordx4 v[44:47], v[12:13], off
	global_load_dwordx4 v[48:51], v[12:13], off offset:16
	v_lshl_add_u64 v[8:9], v[8:9], 0, s[44:45]
	v_lshl_add_u64 v[2:3], v[2:3], 0, s[12:13]
	v_cmp_ge_u64_e32 vcc, s[4:5], v[8:9]
	v_lshl_add_u64 v[12:13], v[2:3], 0, s[10:11]
	s_nop 1
	v_cndmask_b32_e64 v15, 0, 1, vcc
	v_cndmask_b32_e32 v12, v16, v12, vcc
	v_cndmask_b32_e32 v13, v17, v13, vcc
	v_add_u32_e32 v14, v14, v15
	global_load_dwordx4 v[52:55], v[12:13], off
	global_load_dwordx4 v[56:59], v[12:13], off offset:16
	v_lshl_add_u64 v[8:9], v[8:9], 0, s[44:45]
	v_lshl_add_u64 v[2:3], v[2:3], 0, s[12:13]
	v_cmp_ge_u64_e32 vcc, s[4:5], v[8:9]
	v_lshl_add_u64 v[12:13], v[2:3], 0, s[10:11]
	s_nop 1
	v_cndmask_b32_e64 v15, 0, 1, vcc
	v_cndmask_b32_e32 v12, v16, v12, vcc
	v_cndmask_b32_e32 v13, v17, v13, vcc
	v_add_u32_e32 v14, v14, v15
	global_load_dwordx4 v[60:63], v[12:13], off
	global_load_dwordx4 v[64:67], v[12:13], off offset:16
	v_lshl_add_u64 v[8:9], v[8:9], 0, s[44:45]
	v_lshl_add_u64 v[2:3], v[2:3], 0, s[12:13]
	v_cmp_ge_u64_e32 vcc, s[4:5], v[8:9]
	v_lshl_add_u64 v[12:13], v[2:3], 0, s[10:11]
	s_nop 1
	v_cndmask_b32_e64 v15, 0, 1, vcc
	v_cndmask_b32_e32 v12, v16, v12, vcc
	v_cndmask_b32_e32 v13, v17, v13, vcc
	v_add_u32_e32 v14, v14, v15
	global_load_dwordx4 v[68:71], v[12:13], off
	global_load_dwordx4 v[72:75], v[12:13], off offset:16
	v_lshl_add_u64 v[8:9], v[8:9], 0, s[44:45]
	v_lshl_add_u64 v[2:3], v[2:3], 0, s[12:13]
	v_cmp_ge_u64_e32 vcc, s[4:5], v[8:9]
	v_lshl_add_u64 v[12:13], v[2:3], 0, s[10:11]
	s_nop 1
	v_cndmask_b32_e64 v15, 0, 1, vcc
	v_cndmask_b32_e32 v12, v16, v12, vcc
	v_cndmask_b32_e32 v13, v17, v13, vcc
	v_add_u32_e32 v14, v14, v15
	global_load_dwordx4 v[76:79], v[12:13], off
	global_load_dwordx4 v[80:83], v[12:13], off offset:16
	v_lshl_add_u64 v[8:9], v[8:9], 0, s[44:45]
	v_lshl_add_u64 v[2:3], v[2:3], 0, s[12:13]
	v_cmp_ge_u64_e32 vcc, s[4:5], v[8:9]
	v_lshl_add_u64 v[12:13], v[2:3], 0, s[10:11]
	s_nop 1
	v_cndmask_b32_e64 v15, 0, 1, vcc
	v_cndmask_b32_e32 v12, v16, v12, vcc
	v_cndmask_b32_e32 v13, v17, v13, vcc
	v_add_u32_e32 v14, v14, v15
	global_load_dwordx4 v[84:87], v[12:13], off
	global_load_dwordx4 v[88:91], v[12:13], off offset:16
	v_lshl_add_u64 v[8:9], v[8:9], 0, s[44:45]
	v_lshl_add_u64 v[2:3], v[2:3], 0, s[12:13]
	v_cmp_ge_u64_e32 vcc, s[4:5], v[8:9]
	s_and_b64 s[4:5], s[6:7], vcc
	v_cmp_lt_u32_e32 vcc, 0, v14
	s_and_b64 exec, s[6:7], vcc
	s_waitcnt vmcnt(16)
	v_cvt_pk_bf16_f32 v92, v20, v21
	v_cvt_pk_bf16_f32 v93, v22, v23
	v_cvt_pk_bf16_f32 v94, v24, v25
	v_cvt_pk_bf16_f32 v95, v26, v27
	global_store_dwordx4 v[10:11], v[92:95], off
	v_lshl_add_u64 v[10:11], v[10:11], 0, s[8:9]
	v_cmp_lt_u32_e32 vcc, 1, v14
	s_and_b64 exec, s[6:7], vcc
	s_waitcnt vmcnt(15)
	v_cvt_pk_bf16_f32 v92, v28, v29
	v_cvt_pk_bf16_f32 v93, v30, v31
	v_cvt_pk_bf16_f32 v94, v32, v33
	v_cvt_pk_bf16_f32 v95, v34, v35
	global_store_dwordx4 v[10:11], v[92:95], off
	v_lshl_add_u64 v[10:11], v[10:11], 0, s[8:9]
	v_cmp_lt_u32_e32 vcc, 2, v14
	s_and_b64 exec, s[6:7], vcc
	s_waitcnt vmcnt(14)
	v_cvt_pk_bf16_f32 v92, v36, v37
	v_cvt_pk_bf16_f32 v93, v38, v39
	v_cvt_pk_bf16_f32 v94, v40, v41
	v_cvt_pk_bf16_f32 v95, v42, v43
	global_store_dwordx4 v[10:11], v[92:95], off
	v_lshl_add_u64 v[10:11], v[10:11], 0, s[8:9]
	v_cmp_lt_u32_e32 vcc, 3, v14
	s_and_b64 exec, s[6:7], vcc
	s_waitcnt vmcnt(13)
	v_cvt_pk_bf16_f32 v92, v44, v45
	v_cvt_pk_bf16_f32 v93, v46, v47
	v_cvt_pk_bf16_f32 v94, v48, v49
	v_cvt_pk_bf16_f32 v95, v50, v51
	global_store_dwordx4 v[10:11], v[92:95], off
	v_lshl_add_u64 v[10:11], v[10:11], 0, s[8:9]
	v_cmp_lt_u32_e32 vcc, 4, v14
	s_and_b64 exec, s[6:7], vcc
	s_waitcnt vmcnt(12)
	v_cvt_pk_bf16_f32 v92, v52, v53
	v_cvt_pk_bf16_f32 v93, v54, v55
	v_cvt_pk_bf16_f32 v94, v56, v57
	v_cvt_pk_bf16_f32 v95, v58, v59
	global_store_dwordx4 v[10:11], v[92:95], off
	v_lshl_add_u64 v[10:11], v[10:11], 0, s[8:9]
	v_cmp_lt_u32_e32 vcc, 5, v14
	s_and_b64 exec, s[6:7], vcc
	s_waitcnt vmcnt(11)
	v_cvt_pk_bf16_f32 v92, v60, v61
	v_cvt_pk_bf16_f32 v93, v62, v63
	v_cvt_pk_bf16_f32 v94, v64, v65
	v_cvt_pk_bf16_f32 v95, v66, v67
	global_store_dwordx4 v[10:11], v[92:95], off
	v_lshl_add_u64 v[10:11], v[10:11], 0, s[8:9]
	v_cmp_lt_u32_e32 vcc, 6, v14
	s_and_b64 exec, s[6:7], vcc
	s_waitcnt vmcnt(10)
	v_cvt_pk_bf16_f32 v92, v68, v69
	v_cvt_pk_bf16_f32 v93, v70, v71
	v_cvt_pk_bf16_f32 v94, v72, v73
	v_cvt_pk_bf16_f32 v95, v74, v75
	global_store_dwordx4 v[10:11], v[92:95], off
	v_lshl_add_u64 v[10:11], v[10:11], 0, s[8:9]
	v_cmp_lt_u32_e32 vcc, 7, v14
	s_and_b64 exec, s[6:7], vcc
	s_waitcnt vmcnt(9)
	v_cvt_pk_bf16_f32 v92, v76, v77
	v_cvt_pk_bf16_f32 v93, v78, v79
	v_cvt_pk_bf16_f32 v94, v80, v81
	v_cvt_pk_bf16_f32 v95, v82, v83
	global_store_dwordx4 v[10:11], v[92:95], off
	v_lshl_add_u64 v[10:11], v[10:11], 0, s[8:9]
	v_cmp_lt_u32_e32 vcc, 8, v14
	s_and_b64 exec, s[6:7], vcc
	s_waitcnt vmcnt(8)
	v_cvt_pk_bf16_f32 v92, v84, v85
	v_cvt_pk_bf16_f32 v93, v86, v87
	v_cvt_pk_bf16_f32 v94, v88, v89
	v_cvt_pk_bf16_f32 v95, v90, v91
	global_store_dwordx4 v[10:11], v[92:95], off
	v_lshl_add_u64 v[10:11], v[10:11], 0, s[8:9]
	s_mov_b64 exec, s[4:5]
	s_cbranch_execnz .Lpcv_pass
